# phase 0 uses the XCD-hierarchical counter barrier instead of the cooperative-groups grid sync
# speedup vs baseline: 1.0098x; 1.0024x over previous
; #define LAS __attribute__((address_space(3)))
; __device__ __forceinline__ unsigned xb_add(unsigned* p, unsigned v) { return __hip_atomic_fetch_add(p, v, __ATOMIC_RELAXED, __HIP_MEMORY_SCOPE_AGENT); }
; __device__ __forceinline__ unsigned xb_xcc_id() { return (unsigned)__builtin_amdgcn_s_getreg((3 << 11) | 20) & 0xFu; }
; __device__ __forceinline__ void xcd_barrier(unsigned* bar, volatile LAS unsigned* st, const unsigned total) {
;     asm volatile("s_waitcnt vmcnt(0)" ::: "memory");
;     __syncthreads();
;     if (threadIdx.x == 0) {
;         const unsigned x = xb_xcc_id();
;         __builtin_amdgcn_s_waitcnt(0);
;         unsigned nloc = st[0], nx = st[1];
;         if (nloc == 0u) { xcd_barrier_complete(bar, x, nloc, nx, total); st[0] = nloc; st[1] = nx; }
;         const unsigned old = xb_add(&bar[XB_XSUB(x)], 1u);
; __global__ void __launch_bounds__(512) mega(Params P) {
;     ...
;         if (ph == 0) grid.sync();
;         else xcd_barrier((unsigned*)(P.ws + WS_XBAR), xst, gridDim.x);
.LBB0_778:
	s_waitcnt vmcnt(0)
	s_waitcnt lgkmcnt(0)
	s_barrier
	s_mov_b64 s[4:5], exec
	v_readlane_b32 s6, v252, 6
	v_readlane_b32 s7, v252, 7
	s_and_b64 s[6:7], s[4:5], s[6:7]
	s_mov_b64 exec, s[6:7]
	s_cbranch_execz .LBB0_832
	v_readlane_b32 s6, v255, 12
	s_getreg_b32 s1, hwreg(HW_REG_XCC_ID, 0, 4)
	s_waitcnt vmcnt(0) expcnt(0) lgkmcnt(0)
	v_mov_b32_e32 v0, s6
	ds_read_b32 v3, v0
	v_readlane_b32 s6, v255, 13
	s_and_b32 s1, s1, 15
	s_waitcnt lgkmcnt(0)
	v_cmp_ne_u32_e32 vcc, 0, v3
	v_mov_b32_e32 v0, s6
	ds_read_b32 v2, v0
	s_cbranch_vccnz .LBB0_796
	s_mov_b32 s12, 1
	s_branch .LBB0_783
